# conv-FFN epilogue: mask-free copy of the 4-row loop for tiles without a sequence boundary in their row range (tap masks are exactly 1.0 there)
# speedup vs baseline: 1.0102x; 1.0012x over previous
; template <int EPI>
; DI void phase_gemm(const Params& p, const GemmArgs& ga, char* lds) {
;     ...
;         const int R0 = 1 + seg * 16;
;         const int Rend = (R0 + 16 < 255) ? (R0 + 16) : 255;
;         auto ld4 = [&](const char* b_, int R) -> float4 {
;           const u32x2 u = *(const u32x2*)(b_ + R * RS);
;           float4 f = {__uint_as_float(u.x << 16), __uint_as_float(u.x & 0xffff0000u), __uint_as_float(u.y << 16), __uint_as_float(u.y & 0xffff0000u)};
;           return f;
;         };
;         float4 pg = ld4(gbase, R0 - 1), pvv = ld4(vbase, R0 - 1);
;         float4 cg_ = ld4(gbase, R0), cv_ = ld4(vbase, R0);
;         u16* Aout = (u16*)(p.ws + OFF_BIG) + (ptrdiff_t)(tokbase + pos0) * DFF + ch;
; #pragma unroll 4
;         for (int R = R0; R < Rend; ++R) {
;           const float4 ng = ld4(gbase, R + 1), nv = ld4(vbase, R + 1);
;           if (pos0 + R < S) {
.LBB0_68:
	s_or_b64 exec, exec, s[14:15]
	s_and_b64 exec, exec, s[8:9]
	s_cbranch_execz .LBB0_54
	s_mul_i32 s10, s20, 0x1600
	s_mul_hi_i32 s11, s20, 0x1600
	s_add_u32 s10, s2, s10
	s_addc_u32 s11, s3, s11
	s_add_i32 s14, s27, -2
	v_lshl_add_u64 v[38:39], s[10:11], 0, v[46:47]
	s_mul_hi_i32 s10, s14, 0x1600
	s_mul_i32 s11, s14, 0x1600
	v_add_u32_e32 v48, 1, v0
	v_mov_b32_e32 v42, s11
	v_mov_b32_e32 v43, s10
	v_mad_i64_i32 v[48:49], s[10:11], v48, s36, 0
	v_mad_i64_i32 v[42:43], s[10:11], v0, s36, v[42:43]
	v_readlane_b32 s16, v254, 43
	v_mad_i64_i32 v[48:49], s[10:11], s14, v216, v[48:49]
	v_lshl_add_u64 v[42:43], v[42:43], 0, v[46:47]
	v_readlane_b32 s17, v254, 44
	v_lshl_add_u64 v[46:47], v[48:49], 0, v[46:47]
	v_mad_u64_u32 v[48:49], s[10:11], v0, s35, v[156:157]
	v_lshl_add_u64 v[42:43], s[16:17], 0, v[42:43]
	v_lshl_add_u64 v[46:47], s[16:17], 0, v[46:47]
	s_mov_b64 s[14:15], 0
	s_waitcnt vmcnt(0)
	s_ashr_i32 s10, s20, 11
	s_add_i32 s11, s20, 0xff
	s_ashr_i32 s11, s11, 11
	s_cmp_eq_u32 s10, s11
	s_cbranch_scc1 .Lcf0_h
	s_branch .LBB0_71

; DI float fexp2(float x) { return __builtin_amdgcn_exp2f(x); }
; template <int EPI>
; DI void phase_gemm(const Params& p, const GemmArgs& ga, char* lds) {
;     ...
; #pragma unroll 4
;         for (int R = R0; R < Rend; ++R) {
;           const float4 ng = ld4(gbase, R + 1), nv = ld4(vbase, R + 1);
;           if (pos0 + R < S) {
;             const int tflat = pos0 + R;
;             const int ps = (tflat < NTOK_P) ? (tflat & (SP - 1)) : ((tflat - NTOK_P) & (SS - 1));
;             const int Ss = (tflat < NTOK_P) ? SP : SS;
;             const float mp = (ps == 0) ? 0.f : 1.f;
;             const float mn = (ps == Ss - 1) ? 0.f : 1.f;
;             float g[4], v[4];
;             g[0] = mp * pg.x * wg[0].x + cg_.x * wg[1].x + mn * ng.x * wg[2].x + bg.x;
;             g[1] = mp * pg.y * wg[0].y + cg_.y * wg[1].y + mn * ng.y * wg[2].y + bg.y;
;             g[2] = mp * pg.z * wg[0].z + cg_.z * wg[1].z + mn * ng.z * wg[2].z + bg.z;
;             g[3] = mp * pg.w * wg[0].w + cg_.w * wg[1].w + mn * ng.w * wg[2].w + bg.w;
;             v[0] = mp * pvv.x * wv[0].x + cv_.x * wv[1].x + mn * nv.x * wv[2].x + bv.x;
;             v[1] = mp * pvv.y * wv[0].y + cv_.y * wv[1].y + mn * nv.y * wv[2].y + bv.y;
;             v[2] = mp * pvv.z * wv[0].z + cv_.z * wv[1].z + mn * nv.z * wv[2].z + bv.z;
;             v[3] = mp * pvv.w * wv[0].w + cv_.w * wv[1].w + mn * nv.w * wv[2].w + bv.w;
;             float a_[4];
; #pragma unroll
;             for (int e = 0; e < 4; ++e) a_[e] = g[e] * __builtin_amdgcn_rcpf(1.f + fexp2(-1.4426950408889634f * g[e])) * v[e];
;             u32x2 ov = {pk_bf16(a_[0], a_[1]), pk_bf16(a_[2], a_[3])};
;             *(u32x2*)(Aout + (ptrdiff_t)R * DFF) = ov;
;           }
;           pg = cg_; pvv = cv_; cg_ = ng; cv_ = nv;
;         }
.LBB0_77:
	s_or_b64 exec, exec, s[16:17]
	ds_read2_b64 v[34:37], v48 offset0:195 offset1:227
	v_add_u32_e32 v49, 2, v49
	v_cmp_gt_i32_e64 s[10:11], s33, v49
	s_waitcnt lgkmcnt(0)
	v_lshlrev_b32_e32 v40, 16, v34
	v_and_b32_e32 v41, 0xffff0000, v34
	v_lshlrev_b32_e32 v34, 16, v35
	v_and_b32_e32 v35, 0xffff0000, v35
	v_lshlrev_b32_e32 v44, 16, v36
	v_and_b32_e32 v45, 0xffff0000, v36
	v_lshlrev_b32_e32 v36, 16, v37
	v_and_b32_e32 v37, 0xffff0000, v37
	s_and_saveexec_b64 s[16:17], s[10:11]
	s_cbranch_execz .LBB0_70
	v_cmp_gt_i32_e64 s[10:11], s48, v49
	v_add_u32_e32 v65, 3, v0
	v_pk_mul_f32 v[68:69], v[10:11], v[56:57]
	v_cndmask_b32_e64 v61, v217, v218, s[10:11]
	v_and_b32_e32 v49, v61, v49
	v_cmp_eq_u32_e64 s[10:11], 0, v49
	v_pk_mul_f32 v[72:73], v[12:13], v[52:53]
	s_nop 0
	v_cndmask_b32_e64 v60, 1.0, 0, s[10:11]
	v_cmp_eq_u32_e64 s[10:11], v49, v61
	v_pk_mul_f32 v[66:67], v[60:61], v[66:67] op_sel_hi:[0,1]
	v_pk_fma_f32 v[66:67], v[2:3], v[66:67], v[68:69]
	v_cndmask_b32_e64 v64, 1.0, 0, s[10:11]
	v_pk_mul_f32 v[68:69], v[64:65], v[40:41] op_sel_hi:[0,1]
	v_pk_fma_f32 v[66:67], v[18:19], v[68:69], v[66:67]
	v_pk_mul_f32 v[68:69], v[60:61], v[70:71] op_sel_hi:[0,1]
	v_pk_add_f32 v[66:67], v[26:27], v[66:67]
	v_pk_mul_f32 v[68:69], v[6:7], v[68:69]
	v_mul_f32_e32 v49, 0xbfb8aa3b, v66
	v_exp_f32_e32 v49, v49
	v_pk_fma_f32 v[68:69], v[14:15], v[54:55], v[68:69]
	v_pk_mul_f32 v[70:71], v[64:65], v[44:45] op_sel_hi:[0,1]
	v_pk_fma_f32 v[68:69], v[22:23], v[70:71], v[68:69]
	v_add_f32_e32 v49, 1.0, v49
	v_rcp_f32_e32 v70, v49
	v_mul_f32_e32 v49, 0xbfb8aa3b, v67
	v_exp_f32_e32 v49, v49
	v_pk_add_f32 v[68:69], v[30:31], v[68:69]
	v_pk_mul_f32 v[58:59], v[60:61], v[58:59] op_sel_hi:[0,1]
	v_pk_fma_f32 v[58:59], v[4:5], v[58:59], v[72:73]
	v_add_f32_e32 v49, 1.0, v49
	v_rcp_f32_e32 v71, v49
	v_pk_mul_f32 v[60:61], v[60:61], v[62:63] op_sel_hi:[0,1]
	v_pk_mul_f32 v[60:61], v[8:9], v[60:61]
	v_pk_mul_f32 v[62:63], v[64:65], v[36:37] op_sel_hi:[0,1]
	v_pk_mul_f32 v[66:67], v[66:67], v[70:71]
	v_pk_fma_f32 v[60:61], v[16:17], v[50:51], v[60:61]
	v_pk_mul_f32 v[66:67], v[68:69], v[66:67]
	v_pk_mul_f32 v[68:69], v[64:65], v[34:35] op_sel_hi:[0,1]
	v_pk_fma_f32 v[58:59], v[20:21], v[68:69], v[58:59]
	v_pk_fma_f32 v[60:61], v[24:25], v[62:63], v[60:61]
	v_pk_add_f32 v[58:59], v[28:29], v[58:59]
	v_pk_add_f32 v[60:61], v[32:33], v[60:61]
	v_mul_f32_e32 v49, 0xbfb8aa3b, v58
	v_exp_f32_e32 v49, v49
	s_nop 0
	v_add_f32_e32 v49, 1.0, v49
	v_rcp_f32_e32 v62, v49
	v_mul_f32_e32 v49, 0xbfb8aa3b, v59
	v_exp_f32_e32 v49, v49
	s_nop 0
	v_add_f32_e32 v49, 1.0, v49
	v_rcp_f32_e32 v63, v49
	s_nop 0
	v_pk_mul_f32 v[58:59], v[58:59], v[62:63]
	s_nop 0
	v_pk_mul_f32 v[58:59], v[60:61], v[58:59]
	v_cvt_pk_bf16_f32 v60, v66, v67
	v_cvt_pk_bf16_f32 v61, v58, v59
	v_mad_i64_i32 v[58:59], s[10:11], v65, s36, v[38:39]
	global_store_dwordx2 v[58:59], v[60:61], off
	s_branch .LBB0_70
.Lcf0_l:
	s_or_b64 exec, exec, s[16:17]
	v_add_u32_e32 v0, 4, v0
	v_cmp_ge_i32_e64 s[10:11], v0, v170
	v_lshl_add_u64 v[42:43], v[42:43], 0, s[86:87]
	v_lshl_add_u64 v[46:47], v[46:47], 0, s[86:87]
	s_or_b64 s[14:15], s[10:11], s[14:15]
	v_add_u32_e32 v48, 0x820, v48
	s_andn2_b64 exec, exec, s[14:15]
	s_cbranch_execz .LBB0_54
.Lcf0_h:
	ds_read2_b64 v[60:63], v48 offset1:32
	v_add_u32_e32 v49, s27, v0
	v_add_u32_e32 v58, -1, v49
	v_cmp_gt_i32_e64 s[10:11], s33, v58
	s_waitcnt lgkmcnt(0)
	v_lshlrev_b32_e32 v68, 16, v60
	v_and_b32_e32 v69, 0xffff0000, v60
	v_lshlrev_b32_e32 v60, 16, v61
	v_and_b32_e32 v61, 0xffff0000, v61
	v_lshlrev_b32_e32 v72, 16, v62
	v_and_b32_e32 v73, 0xffff0000, v62
	v_lshlrev_b32_e32 v64, 16, v63
	v_and_b32_e32 v65, 0xffff0000, v63
	s_and_saveexec_b64 s[16:17], s[10:11]
	s_cbranch_execz .Lcf0_s0
	v_pk_mul_f32 v[66:67], v[10:11], v[40:41]
	v_pk_mul_f32 v[70:71], v[12:13], v[34:35]
	v_pk_fma_f32 v[56:57], v[2:3], v[56:57], v[66:67]
	v_pk_fma_f32 v[56:57], v[18:19], v[68:69], v[56:57]
	v_pk_mul_f32 v[54:55], v[6:7], v[54:55]
	v_pk_add_f32 v[56:57], v[26:27], v[56:57]
	v_pk_fma_f32 v[54:55], v[14:15], v[44:45], v[54:55]
	v_mul_f32_e32 v59, 0xbfb8aa3b, v56
	v_exp_f32_e32 v59, v59
	v_pk_fma_f32 v[54:55], v[22:23], v[72:73], v[54:55]
	v_add_f32_e32 v59, 1.0, v59
	v_rcp_f32_e32 v66, v59
	v_mul_f32_e32 v59, 0xbfb8aa3b, v57
	v_exp_f32_e32 v59, v59
	v_pk_add_f32 v[54:55], v[30:31], v[54:55]
	v_add_f32_e32 v59, 1.0, v59
	v_rcp_f32_e32 v67, v59
	v_pk_fma_f32 v[52:53], v[4:5], v[52:53], v[70:71]
	v_pk_mul_f32 v[56:57], v[56:57], v[66:67]
	v_pk_mul_f32 v[50:51], v[8:9], v[50:51]
	v_pk_mul_f32 v[54:55], v[54:55], v[56:57]
	v_pk_fma_f32 v[52:53], v[20:21], v[60:61], v[52:53]
	v_pk_fma_f32 v[50:51], v[16:17], v[36:37], v[50:51]
	v_pk_add_f32 v[52:53], v[28:29], v[52:53]
	v_pk_fma_f32 v[50:51], v[24:25], v[64:65], v[50:51]
	v_mul_f32_e32 v56, 0xbfb8aa3b, v52
	v_mul_f32_e32 v57, 0xbfb8aa3b, v53
	v_exp_f32_e32 v56, v56
	v_exp_f32_e32 v57, v57
	v_pk_add_f32 v[50:51], v[32:33], v[50:51]
	v_add_f32_e32 v56, 1.0, v56
	v_add_f32_e32 v57, 1.0, v57
	v_rcp_f32_e32 v56, v56
	v_rcp_f32_e32 v57, v57
	s_nop 0
	v_pk_mul_f32 v[52:53], v[52:53], v[56:57]
	s_nop 0
	v_pk_mul_f32 v[50:51], v[50:51], v[52:53]
	v_cvt_pk_bf16_f32 v52, v54, v55
	v_cvt_pk_bf16_f32 v53, v50, v51
	global_store_dwordx2 v[42:43], v[52:53], off
; DI float fexp2(float x) { return __builtin_amdgcn_exp2f(x); }
; template <int EPI>
; DI void phase_gemm(const Params& p, const GemmArgs& ga, char* lds) {
;     ...
; #pragma unroll 4
;         for (int R = R0; R < Rend; ++R) {
;           const float4 ng = ld4(gbase, R + 1), nv = ld4(vbase, R + 1);
;           if (pos0 + R < S) {
;             const int tflat = pos0 + R;
;             const int ps = (tflat < NTOK_P) ? (tflat & (SP - 1)) : ((tflat - NTOK_P) & (SS - 1));
;             const int Ss = (tflat < NTOK_P) ? SP : SS;
;             const float mp = (ps == 0) ? 0.f : 1.f;
;             const float mn = (ps == Ss - 1) ? 0.f : 1.f;
;             float g[4], v[4];
;             g[0] = mp * pg.x * wg[0].x + cg_.x * wg[1].x + mn * ng.x * wg[2].x + bg.x;
;             g[1] = mp * pg.y * wg[0].y + cg_.y * wg[1].y + mn * ng.y * wg[2].y + bg.y;
;             g[2] = mp * pg.z * wg[0].z + cg_.z * wg[1].z + mn * ng.z * wg[2].z + bg.z;
;             g[3] = mp * pg.w * wg[0].w + cg_.w * wg[1].w + mn * ng.w * wg[2].w + bg.w;
;             v[0] = mp * pvv.x * wv[0].x + cv_.x * wv[1].x + mn * nv.x * wv[2].x + bv.x;
;             v[1] = mp * pvv.y * wv[0].y + cv_.y * wv[1].y + mn * nv.y * wv[2].y + bv.y;
;             v[2] = mp * pvv.z * wv[0].z + cv_.z * wv[1].z + mn * nv.z * wv[2].z + bv.z;
;             v[3] = mp * pvv.w * wv[0].w + cv_.w * wv[1].w + mn * nv.w * wv[2].w + bv.w;
;             float a_[4];
; #pragma unroll
;             for (int e = 0; e < 4; ++e) a_[e] = g[e] * __builtin_amdgcn_rcpf(1.f + fexp2(-1.4426950408889634f * g[e])) * v[e];
;             u32x2 ov = {pk_bf16(a_[0], a_[1]), pk_bf16(a_[2], a_[3])};
;             *(u32x2*)(Aout + (ptrdiff_t)R * DFF) = ov;
;           }
;           pg = cg_; pvv = cv_; cg_ = ng; cv_ = nv;
;         }
.Lcf0_s0:
	s_or_b64 exec, exec, s[16:17]
	ds_read2_b64 v[50:53], v48 offset0:65 offset1:97
	v_cmp_gt_i32_e64 s[10:11], s33, v49
	s_waitcnt lgkmcnt(0)
	v_lshlrev_b32_e32 v66, 16, v50
	v_and_b32_e32 v67, 0xffff0000, v50
	v_lshlrev_b32_e32 v58, 16, v51
	v_and_b32_e32 v59, 0xffff0000, v51
	v_lshlrev_b32_e32 v70, 16, v52
	v_and_b32_e32 v71, 0xffff0000, v52
	v_lshlrev_b32_e32 v62, 16, v53
	v_and_b32_e32 v63, 0xffff0000, v53
	s_and_saveexec_b64 s[16:17], s[10:11]
	s_cbranch_execz .Lcf0_s1
	v_pk_mul_f32 v[54:55], v[10:11], v[68:69]
	v_pk_mul_f32 v[56:57], v[12:13], v[60:61]
	v_pk_fma_f32 v[40:41], v[2:3], v[40:41], v[54:55]
	v_pk_fma_f32 v[40:41], v[18:19], v[66:67], v[40:41]
	v_pk_mul_f32 v[44:45], v[6:7], v[44:45]
	v_pk_add_f32 v[40:41], v[26:27], v[40:41]
	v_pk_fma_f32 v[44:45], v[14:15], v[72:73], v[44:45]
	v_mul_f32_e32 v51, 0xbfb8aa3b, v40
	v_exp_f32_e32 v51, v51
	v_pk_fma_f32 v[44:45], v[22:23], v[70:71], v[44:45]
	v_add_f32_e32 v51, 1.0, v51
	v_rcp_f32_e32 v54, v51
	v_mul_f32_e32 v51, 0xbfb8aa3b, v41
	v_exp_f32_e32 v51, v51
	v_pk_add_f32 v[44:45], v[30:31], v[44:45]
	v_add_f32_e32 v51, 1.0, v51
	v_rcp_f32_e32 v55, v51
	v_pk_fma_f32 v[34:35], v[4:5], v[34:35], v[56:57]
	v_pk_mul_f32 v[40:41], v[40:41], v[54:55]
	v_pk_mul_f32 v[36:37], v[8:9], v[36:37]
	v_pk_mul_f32 v[40:41], v[44:45], v[40:41]
	v_pk_fma_f32 v[34:35], v[20:21], v[58:59], v[34:35]
	v_pk_fma_f32 v[36:37], v[16:17], v[64:65], v[36:37]
	v_pk_add_f32 v[34:35], v[28:29], v[34:35]
	v_pk_fma_f32 v[36:37], v[24:25], v[62:63], v[36:37]
	v_mul_f32_e32 v44, 0xbfb8aa3b, v34
	v_mul_f32_e32 v45, 0xbfb8aa3b, v35
	v_exp_f32_e32 v44, v44
	v_exp_f32_e32 v45, v45
	v_pk_add_f32 v[36:37], v[32:33], v[36:37]
	v_add_f32_e32 v44, 1.0, v44
	v_add_f32_e32 v45, 1.0, v45
	v_rcp_f32_e32 v44, v44
	v_rcp_f32_e32 v45, v45
	s_nop 0
	v_pk_mul_f32 v[34:35], v[34:35], v[44:45]
	s_nop 0
	v_pk_mul_f32 v[34:35], v[36:37], v[34:35]
	v_cvt_pk_bf16_f32 v36, v40, v41
	v_cvt_pk_bf16_f32 v37, v34, v35
	global_store_dwordx2 v[46:47], v[36:37], off
.Lcf0_s1:
	s_or_b64 exec, exec, s[16:17]
	ds_read2_b64 v[34:37], v48 offset0:130 offset1:162
	s_waitcnt lgkmcnt(0)
	v_lshlrev_b32_e32 v56, 16, v34
	v_and_b32_e32 v57, 0xffff0000, v34
	v_add_u32_e32 v34, 1, v49
	v_lshlrev_b32_e32 v52, 16, v35
	v_and_b32_e32 v53, 0xffff0000, v35
	v_lshlrev_b32_e32 v54, 16, v36
	v_and_b32_e32 v55, 0xffff0000, v36
	v_lshlrev_b32_e32 v50, 16, v37
	v_and_b32_e32 v51, 0xffff0000, v37
	v_cmp_gt_i32_e64 s[10:11], s33, v34
	s_and_saveexec_b64 s[16:17], s[10:11]
	s_cbranch_execz .Lcf0_s2
	v_pk_mul_f32 v[40:41], v[10:11], v[66:67]
	v_pk_mul_f32 v[44:45], v[12:13], v[58:59]
	v_add_u32_e32 v74, 2, v0
	v_pk_fma_f32 v[40:41], v[2:3], v[68:69], v[40:41]
	v_pk_fma_f32 v[40:41], v[18:19], v[56:57], v[40:41]
	v_mov_b64_e32 v[68:69], v[72:73]
	v_pk_add_f32 v[40:41], v[26:27], v[40:41]
	v_pk_mul_f32 v[68:69], v[6:7], v[68:69]
	v_mul_f32_e32 v35, 0xbfb8aa3b, v40
	v_exp_f32_e32 v35, v35
	v_pk_fma_f32 v[68:69], v[14:15], v[70:71], v[68:69]
	v_pk_fma_f32 v[68:69], v[22:23], v[54:55], v[68:69]
	v_add_f32_e32 v35, 1.0, v35
	v_rcp_f32_e32 v72, v35
	v_mul_f32_e32 v35, 0xbfb8aa3b, v41
	v_exp_f32_e32 v35, v35
	v_pk_add_f32 v[68:69], v[30:31], v[68:69]
	v_add_f32_e32 v35, 1.0, v35
	v_rcp_f32_e32 v73, v35
	v_pk_fma_f32 v[44:45], v[4:5], v[60:61], v[44:45]
	v_mov_b64_e32 v[60:61], v[52:53]
	v_mov_b64_e32 v[34:35], v[64:65]
	v_pk_fma_f32 v[44:45], v[20:21], v[60:61], v[44:45]
	v_pk_mul_f32 v[34:35], v[8:9], v[34:35]
	v_pk_add_f32 v[44:45], v[28:29], v[44:45]
	v_pk_fma_f32 v[34:35], v[16:17], v[62:63], v[34:35]
	v_pk_fma_f32 v[34:35], v[24:25], v[50:51], v[34:35]
	v_mul_f32_e32 v36, 0xbfb8aa3b, v44
	v_mul_f32_e32 v37, 0xbfb8aa3b, v45
	v_exp_f32_e32 v36, v36
	v_exp_f32_e32 v37, v37
	v_pk_mul_f32 v[40:41], v[40:41], v[72:73]
	v_pk_add_f32 v[34:35], v[32:33], v[34:35]
	v_add_f32_e32 v36, 1.0, v36
	v_add_f32_e32 v37, 1.0, v37
	v_rcp_f32_e32 v36, v36
	v_rcp_f32_e32 v37, v37
	v_pk_mul_f32 v[40:41], v[68:69], v[40:41]
	v_pk_mul_f32 v[36:37], v[44:45], v[36:37]
	s_nop 0
	v_pk_mul_f32 v[34:35], v[34:35], v[36:37]
	v_cvt_pk_bf16_f32 v36, v40, v41
	v_cvt_pk_bf16_f32 v37, v34, v35
	v_mad_i64_i32 v[34:35], s[10:11], v74, s36, v[38:39]
	global_store_dwordx2 v[34:35], v[36:37], off
.Lcf0_s2:
	s_or_b64 exec, exec, s[16:17]
	ds_read2_b64 v[34:37], v48 offset0:195 offset1:227
	v_add_u32_e32 v49, 2, v49
	v_cmp_gt_i32_e64 s[10:11], s33, v49
	s_waitcnt lgkmcnt(0)
	v_lshlrev_b32_e32 v40, 16, v34
	v_and_b32_e32 v41, 0xffff0000, v34
	v_lshlrev_b32_e32 v34, 16, v35
	v_and_b32_e32 v35, 0xffff0000, v35
	v_lshlrev_b32_e32 v44, 16, v36
	v_and_b32_e32 v45, 0xffff0000, v36
	v_lshlrev_b32_e32 v36, 16, v37
	v_and_b32_e32 v37, 0xffff0000, v37
	s_and_saveexec_b64 s[16:17], s[10:11]
	s_cbranch_execz .Lcf0_l
	v_add_u32_e32 v65, 3, v0
	v_pk_mul_f32 v[68:69], v[10:11], v[56:57]
	v_pk_mul_f32 v[72:73], v[12:13], v[52:53]
	v_pk_fma_f32 v[66:67], v[2:3], v[66:67], v[68:69]
	v_pk_fma_f32 v[66:67], v[18:19], v[40:41], v[66:67]
	v_mov_b64_e32 v[68:69], v[70:71]
	v_pk_add_f32 v[66:67], v[26:27], v[66:67]
	v_pk_mul_f32 v[68:69], v[6:7], v[68:69]
	v_mul_f32_e32 v49, 0xbfb8aa3b, v66
	v_exp_f32_e32 v49, v49
	v_pk_fma_f32 v[68:69], v[14:15], v[54:55], v[68:69]
	v_pk_fma_f32 v[68:69], v[22:23], v[44:45], v[68:69]
	v_add_f32_e32 v49, 1.0, v49
	v_rcp_f32_e32 v70, v49
	v_mul_f32_e32 v49, 0xbfb8aa3b, v67
	v_exp_f32_e32 v49, v49
	v_pk_add_f32 v[68:69], v[30:31], v[68:69]
	v_pk_fma_f32 v[58:59], v[4:5], v[58:59], v[72:73]
	v_add_f32_e32 v49, 1.0, v49
	v_rcp_f32_e32 v71, v49
	v_mov_b64_e32 v[60:61], v[62:63]
	v_pk_mul_f32 v[60:61], v[8:9], v[60:61]
	v_pk_mul_f32 v[66:67], v[66:67], v[70:71]
	v_pk_fma_f32 v[60:61], v[16:17], v[50:51], v[60:61]
	v_pk_mul_f32 v[66:67], v[68:69], v[66:67]
	v_mov_b64_e32 v[68:69], v[34:35]
	v_pk_fma_f32 v[58:59], v[20:21], v[68:69], v[58:59]
	v_pk_fma_f32 v[60:61], v[24:25], v[36:37], v[60:61]
	v_pk_add_f32 v[58:59], v[28:29], v[58:59]
	v_pk_add_f32 v[60:61], v[32:33], v[60:61]
	v_mul_f32_e32 v49, 0xbfb8aa3b, v58
	v_exp_f32_e32 v49, v49
	s_nop 0
	v_add_f32_e32 v49, 1.0, v49
	v_rcp_f32_e32 v62, v49
	v_mul_f32_e32 v49, 0xbfb8aa3b, v59
	v_exp_f32_e32 v49, v49
	s_nop 0
	v_add_f32_e32 v49, 1.0, v49
	v_rcp_f32_e32 v63, v49
	s_nop 0
	v_pk_mul_f32 v[58:59], v[58:59], v[62:63]
	s_nop 0
	v_pk_mul_f32 v[58:59], v[60:61], v[58:59]
	v_cvt_pk_bf16_f32 v60, v66, v67
	v_cvt_pk_bf16_f32 v61, v58, v59
	v_mad_i64_i32 v[58:59], s[10:11], v65, s36, v[38:39]
	global_store_dwordx2 v[58:59], v[60:61], off
	s_branch .Lcf0_l

; template <int EPI>
; DI void phase_gemm(const Params& p, const GemmArgs& ga, char* lds) {
;     ...
;         const int R0 = 1 + seg * 16;
;         const int Rend = (R0 + 16 < 255) ? (R0 + 16) : 255;
;         auto ld4 = [&](const char* b_, int R) -> float4 {
;           const u32x2 u = *(const u32x2*)(b_ + R * RS);
;           float4 f = {__uint_as_float(u.x << 16), __uint_as_float(u.x & 0xffff0000u), __uint_as_float(u.y << 16), __uint_as_float(u.y & 0xffff0000u)};
;           return f;
;         };
;         float4 pg = ld4(gbase, R0 - 1), pvv = ld4(vbase, R0 - 1);
;         float4 cg_ = ld4(gbase, R0), cv_ = ld4(vbase, R0);
;         u16* Aout = (u16*)(p.ws + OFF_BIG) + (ptrdiff_t)(tokbase + pos0) * DFF + ch;
; #pragma unroll 4
;         for (int R = R0; R < Rend; ++R) {
;           const float4 ng = ld4(gbase, R + 1), nv = ld4(vbase, R + 1);
;           if (pos0 + R < S) {
.LBB0_179:
	s_or_b64 exec, exec, s[14:15]
	s_and_b64 s[10:11], exec, s[8:9]
	s_mov_b64 s[42:43], 0x3818900
	s_mov_b64 s[40:41], 0x3838900
	s_mov_b64 s[38:39], 0x3858900
	s_mov_b64 s[36:37], 0x27c0080
	s_mov_b64 exec, s[10:11]
	s_cbranch_execz .LBB0_165
	s_mul_i32 s10, s20, 0x1600
	s_mul_hi_i32 s11, s20, 0x1600
	s_add_u32 s10, s2, s10
	s_addc_u32 s11, s3, s11
	s_add_i32 s14, s27, -2
	v_lshl_add_u64 v[38:39], s[10:11], 0, v[46:47]
	s_mul_hi_i32 s10, s14, 0x1600
	s_mul_i32 s11, s14, 0x1600
	v_add_u32_e32 v50, 1, v0
	v_mov_b32_e32 v42, s11
	v_mov_b32_e32 v43, s10
	v_mad_i64_i32 v[50:51], s[10:11], v50, s46, 0
	v_mad_i64_i32 v[42:43], s[10:11], v0, s46, v[42:43]
	v_readlane_b32 s16, v254, 43
	v_mad_i64_i32 v[50:51], s[10:11], s14, v216, v[50:51]
	v_lshl_add_u64 v[42:43], v[42:43], 0, v[46:47]
	v_readlane_b32 s17, v254, 44
	v_lshl_add_u64 v[46:47], v[50:51], 0, v[46:47]
	v_mad_u64_u32 v[50:51], s[10:11], v0, s35, v[156:157]
	v_lshl_add_u64 v[42:43], s[16:17], 0, v[42:43]
	v_lshl_add_u64 v[46:47], s[16:17], 0, v[46:47]
	s_mov_b64 s[14:15], 0
	s_waitcnt vmcnt(0)
	s_ashr_i32 s10, s20, 11
	s_add_i32 s11, s20, 0xff
	s_ashr_i32 s11, s11, 11
	s_cmp_eq_u32 s10, s11
	s_cbranch_scc1 .Lcf1_h
	s_branch .LBB0_182

; DI float fexp2(float x) { return __builtin_amdgcn_exp2f(x); }
; template <int EPI>
; DI void phase_gemm(const Params& p, const GemmArgs& ga, char* lds) {
;     ...
; #pragma unroll 4
;         for (int R = R0; R < Rend; ++R) {
;           const float4 ng = ld4(gbase, R + 1), nv = ld4(vbase, R + 1);
;           if (pos0 + R < S) {
;             const int tflat = pos0 + R;
;             const int ps = (tflat < NTOK_P) ? (tflat & (SP - 1)) : ((tflat - NTOK_P) & (SS - 1));
;             const int Ss = (tflat < NTOK_P) ? SP : SS;
;             const float mp = (ps == 0) ? 0.f : 1.f;
;             const float mn = (ps == Ss - 1) ? 0.f : 1.f;
;             float g[4], v[4];
;             g[0] = mp * pg.x * wg[0].x + cg_.x * wg[1].x + mn * ng.x * wg[2].x + bg.x;
;             g[1] = mp * pg.y * wg[0].y + cg_.y * wg[1].y + mn * ng.y * wg[2].y + bg.y;
;             g[2] = mp * pg.z * wg[0].z + cg_.z * wg[1].z + mn * ng.z * wg[2].z + bg.z;
;             g[3] = mp * pg.w * wg[0].w + cg_.w * wg[1].w + mn * ng.w * wg[2].w + bg.w;
;             v[0] = mp * pvv.x * wv[0].x + cv_.x * wv[1].x + mn * nv.x * wv[2].x + bv.x;
;             v[1] = mp * pvv.y * wv[0].y + cv_.y * wv[1].y + mn * nv.y * wv[2].y + bv.y;
;             v[2] = mp * pvv.z * wv[0].z + cv_.z * wv[1].z + mn * nv.z * wv[2].z + bv.z;
;             v[3] = mp * pvv.w * wv[0].w + cv_.w * wv[1].w + mn * nv.w * wv[2].w + bv.w;
;             float a_[4];
; #pragma unroll
;             for (int e = 0; e < 4; ++e) a_[e] = g[e] * __builtin_amdgcn_rcpf(1.f + fexp2(-1.4426950408889634f * g[e])) * v[e];
;             u32x2 ov = {pk_bf16(a_[0], a_[1]), pk_bf16(a_[2], a_[3])};
;             *(u32x2*)(Aout + (ptrdiff_t)R * DFF) = ov;
;           }
;           pg = cg_; pvv = cv_; cg_ = ng; cv_ = nv;
;         }
.LBB0_188:
	s_or_b64 exec, exec, s[16:17]
	ds_read2_b64 v[34:37], v50 offset0:195 offset1:227
	v_add_u32_e32 v51, 2, v51
	v_cmp_gt_i32_e64 s[10:11], s33, v51
	s_waitcnt lgkmcnt(0)
	v_lshlrev_b32_e32 v40, 16, v34
	v_and_b32_e32 v41, 0xffff0000, v34
	v_lshlrev_b32_e32 v34, 16, v35
	v_and_b32_e32 v35, 0xffff0000, v35
	v_lshlrev_b32_e32 v44, 16, v36
	v_and_b32_e32 v45, 0xffff0000, v36
	v_lshlrev_b32_e32 v36, 16, v37
	v_and_b32_e32 v37, 0xffff0000, v37
	s_and_saveexec_b64 s[16:17], s[10:11]
	s_cbranch_execz .LBB0_181
	v_cmp_gt_i32_e64 s[10:11], s48, v51
	v_add_u32_e32 v65, 3, v0
	v_pk_mul_f32 v[68:69], v[10:11], v[56:57]
	v_cndmask_b32_e64 v61, v217, v218, s[10:11]
	v_and_b32_e32 v51, v61, v51
	v_cmp_eq_u32_e64 s[10:11], 0, v51
	v_pk_mul_f32 v[72:73], v[12:13], v[52:53]
	s_nop 0
	v_cndmask_b32_e64 v60, 1.0, 0, s[10:11]
	v_cmp_eq_u32_e64 s[10:11], v51, v61
	v_pk_mul_f32 v[66:67], v[60:61], v[66:67] op_sel_hi:[0,1]
	v_pk_fma_f32 v[66:67], v[2:3], v[66:67], v[68:69]
	v_cndmask_b32_e64 v64, 1.0, 0, s[10:11]
	v_pk_mul_f32 v[68:69], v[64:65], v[40:41] op_sel_hi:[0,1]
	v_pk_fma_f32 v[66:67], v[18:19], v[68:69], v[66:67]
	v_pk_mul_f32 v[68:69], v[60:61], v[70:71] op_sel_hi:[0,1]
	v_pk_add_f32 v[66:67], v[26:27], v[66:67]
	v_pk_mul_f32 v[68:69], v[6:7], v[68:69]
	v_mul_f32_e32 v51, 0xbfb8aa3b, v66
	v_exp_f32_e32 v51, v51
	v_pk_fma_f32 v[68:69], v[14:15], v[54:55], v[68:69]
	v_pk_mul_f32 v[70:71], v[64:65], v[44:45] op_sel_hi:[0,1]
	v_pk_fma_f32 v[68:69], v[22:23], v[70:71], v[68:69]
	v_add_f32_e32 v51, 1.0, v51
	v_rcp_f32_e32 v70, v51
	v_mul_f32_e32 v51, 0xbfb8aa3b, v67
	v_exp_f32_e32 v51, v51
	v_pk_add_f32 v[68:69], v[30:31], v[68:69]
	v_pk_mul_f32 v[58:59], v[60:61], v[58:59] op_sel_hi:[0,1]
	v_pk_fma_f32 v[58:59], v[4:5], v[58:59], v[72:73]
	v_add_f32_e32 v51, 1.0, v51
	v_rcp_f32_e32 v71, v51
	v_pk_mul_f32 v[60:61], v[60:61], v[62:63] op_sel_hi:[0,1]
	v_pk_mul_f32 v[60:61], v[8:9], v[60:61]
	v_pk_mul_f32 v[62:63], v[64:65], v[36:37] op_sel_hi:[0,1]
	v_pk_mul_f32 v[66:67], v[66:67], v[70:71]
	v_pk_fma_f32 v[60:61], v[16:17], v[48:49], v[60:61]
	v_pk_mul_f32 v[66:67], v[68:69], v[66:67]
	v_pk_mul_f32 v[68:69], v[64:65], v[34:35] op_sel_hi:[0,1]
	v_pk_fma_f32 v[58:59], v[20:21], v[68:69], v[58:59]
	v_pk_fma_f32 v[60:61], v[24:25], v[62:63], v[60:61]
	v_pk_add_f32 v[58:59], v[28:29], v[58:59]
	v_pk_add_f32 v[60:61], v[32:33], v[60:61]
	v_mul_f32_e32 v51, 0xbfb8aa3b, v58
	v_exp_f32_e32 v51, v51
	s_nop 0
	v_add_f32_e32 v51, 1.0, v51
	v_rcp_f32_e32 v62, v51
	v_mul_f32_e32 v51, 0xbfb8aa3b, v59
	v_exp_f32_e32 v51, v51
	s_nop 0
	v_add_f32_e32 v51, 1.0, v51
	v_rcp_f32_e32 v63, v51
	s_nop 0
	v_pk_mul_f32 v[58:59], v[58:59], v[62:63]
	s_nop 0
	v_pk_mul_f32 v[58:59], v[60:61], v[58:59]
	v_cvt_pk_bf16_f32 v60, v66, v67
	v_cvt_pk_bf16_f32 v61, v58, v59
	v_mad_i64_i32 v[58:59], s[10:11], v65, s46, v[38:39]
	global_store_dwordx2 v[58:59], v[60:61], off
	s_branch .LBB0_181
.Lcf1_l:
	s_or_b64 exec, exec, s[16:17]
	v_add_u32_e32 v0, 4, v0
	v_cmp_ge_i32_e64 s[10:11], v0, v170
	v_lshl_add_u64 v[42:43], v[42:43], 0, s[86:87]
	v_lshl_add_u64 v[46:47], v[46:47], 0, s[86:87]
	s_or_b64 s[14:15], s[10:11], s[14:15]
	v_add_u32_e32 v50, 0x820, v50
	s_andn2_b64 exec, exec, s[14:15]
	s_cbranch_execz .LBB0_165
.Lcf1_h:
	ds_read2_b64 v[60:63], v50 offset1:32
	v_add_u32_e32 v51, s27, v0
	v_add_u32_e32 v58, -1, v51
	v_cmp_gt_i32_e64 s[10:11], s33, v58
	s_waitcnt lgkmcnt(0)
	v_lshlrev_b32_e32 v68, 16, v60
	v_and_b32_e32 v69, 0xffff0000, v60
	v_lshlrev_b32_e32 v60, 16, v61
	v_and_b32_e32 v61, 0xffff0000, v61
	v_lshlrev_b32_e32 v72, 16, v62
	v_and_b32_e32 v73, 0xffff0000, v62
	v_lshlrev_b32_e32 v64, 16, v63
	v_and_b32_e32 v65, 0xffff0000, v63
	s_and_saveexec_b64 s[16:17], s[10:11]
	s_cbranch_execz .Lcf1_s0
	v_pk_mul_f32 v[66:67], v[10:11], v[40:41]
	v_pk_mul_f32 v[70:71], v[12:13], v[34:35]
	v_pk_fma_f32 v[56:57], v[2:3], v[56:57], v[66:67]
	v_pk_fma_f32 v[56:57], v[18:19], v[68:69], v[56:57]
	v_pk_mul_f32 v[54:55], v[6:7], v[54:55]
	v_pk_add_f32 v[56:57], v[26:27], v[56:57]
	v_pk_fma_f32 v[54:55], v[14:15], v[44:45], v[54:55]
	v_mul_f32_e32 v59, 0xbfb8aa3b, v56
	v_exp_f32_e32 v59, v59
	v_pk_fma_f32 v[54:55], v[22:23], v[72:73], v[54:55]
	v_add_f32_e32 v59, 1.0, v59
	v_rcp_f32_e32 v66, v59
	v_mul_f32_e32 v59, 0xbfb8aa3b, v57
	v_exp_f32_e32 v59, v59
	v_pk_add_f32 v[54:55], v[30:31], v[54:55]
	v_add_f32_e32 v59, 1.0, v59
	v_rcp_f32_e32 v67, v59
	v_pk_fma_f32 v[52:53], v[4:5], v[52:53], v[70:71]
	v_pk_mul_f32 v[56:57], v[56:57], v[66:67]
	v_pk_mul_f32 v[48:49], v[8:9], v[48:49]
	v_pk_mul_f32 v[54:55], v[54:55], v[56:57]
	v_pk_fma_f32 v[52:53], v[20:21], v[60:61], v[52:53]
	v_pk_fma_f32 v[48:49], v[16:17], v[36:37], v[48:49]
	v_pk_add_f32 v[52:53], v[28:29], v[52:53]
	v_pk_fma_f32 v[48:49], v[24:25], v[64:65], v[48:49]
	v_mul_f32_e32 v56, 0xbfb8aa3b, v52
	v_mul_f32_e32 v57, 0xbfb8aa3b, v53
	v_exp_f32_e32 v56, v56
	v_exp_f32_e32 v57, v57
	v_pk_add_f32 v[48:49], v[32:33], v[48:49]
	v_add_f32_e32 v56, 1.0, v56
	v_add_f32_e32 v57, 1.0, v57
	v_rcp_f32_e32 v56, v56
	v_rcp_f32_e32 v57, v57
	s_nop 0
	v_pk_mul_f32 v[52:53], v[52:53], v[56:57]
	s_nop 0
	v_pk_mul_f32 v[48:49], v[48:49], v[52:53]
	v_cvt_pk_bf16_f32 v52, v54, v55
	v_cvt_pk_bf16_f32 v53, v48, v49
	global_store_dwordx2 v[42:43], v[52:53], off
; DI float fexp2(float x) { return __builtin_amdgcn_exp2f(x); }
; template <int EPI>
; DI void phase_gemm(const Params& p, const GemmArgs& ga, char* lds) {
;     ...
; #pragma unroll 4
;         for (int R = R0; R < Rend; ++R) {
;           const float4 ng = ld4(gbase, R + 1), nv = ld4(vbase, R + 1);
;           if (pos0 + R < S) {
;             const int tflat = pos0 + R;
;             const int ps = (tflat < NTOK_P) ? (tflat & (SP - 1)) : ((tflat - NTOK_P) & (SS - 1));
;             const int Ss = (tflat < NTOK_P) ? SP : SS;
;             const float mp = (ps == 0) ? 0.f : 1.f;
;             const float mn = (ps == Ss - 1) ? 0.f : 1.f;
;             float g[4], v[4];
;             g[0] = mp * pg.x * wg[0].x + cg_.x * wg[1].x + mn * ng.x * wg[2].x + bg.x;
;             g[1] = mp * pg.y * wg[0].y + cg_.y * wg[1].y + mn * ng.y * wg[2].y + bg.y;
;             g[2] = mp * pg.z * wg[0].z + cg_.z * wg[1].z + mn * ng.z * wg[2].z + bg.z;
;             g[3] = mp * pg.w * wg[0].w + cg_.w * wg[1].w + mn * ng.w * wg[2].w + bg.w;
;             v[0] = mp * pvv.x * wv[0].x + cv_.x * wv[1].x + mn * nv.x * wv[2].x + bv.x;
;             v[1] = mp * pvv.y * wv[0].y + cv_.y * wv[1].y + mn * nv.y * wv[2].y + bv.y;
;             v[2] = mp * pvv.z * wv[0].z + cv_.z * wv[1].z + mn * nv.z * wv[2].z + bv.z;
;             v[3] = mp * pvv.w * wv[0].w + cv_.w * wv[1].w + mn * nv.w * wv[2].w + bv.w;
;             float a_[4];
; #pragma unroll
;             for (int e = 0; e < 4; ++e) a_[e] = g[e] * __builtin_amdgcn_rcpf(1.f + fexp2(-1.4426950408889634f * g[e])) * v[e];
;             u32x2 ov = {pk_bf16(a_[0], a_[1]), pk_bf16(a_[2], a_[3])};
;             *(u32x2*)(Aout + (ptrdiff_t)R * DFF) = ov;
;           }
;           pg = cg_; pvv = cv_; cg_ = ng; cv_ = nv;
;         }
.Lcf1_s0:
	s_or_b64 exec, exec, s[16:17]
	ds_read2_b64 v[52:55], v50 offset0:65 offset1:97
	v_cmp_gt_i32_e64 s[10:11], s33, v51
	s_waitcnt lgkmcnt(0)
	v_lshlrev_b32_e32 v66, 16, v52
	v_and_b32_e32 v67, 0xffff0000, v52
	v_lshlrev_b32_e32 v58, 16, v53
	v_and_b32_e32 v59, 0xffff0000, v53
	v_lshlrev_b32_e32 v70, 16, v54
	v_and_b32_e32 v71, 0xffff0000, v54
	v_lshlrev_b32_e32 v62, 16, v55
	v_and_b32_e32 v63, 0xffff0000, v55
	s_and_saveexec_b64 s[16:17], s[10:11]
	s_cbranch_execz .Lcf1_s1
	v_pk_mul_f32 v[54:55], v[10:11], v[68:69]
	v_pk_mul_f32 v[56:57], v[12:13], v[60:61]
	v_pk_fma_f32 v[40:41], v[2:3], v[40:41], v[54:55]
	v_pk_fma_f32 v[40:41], v[18:19], v[66:67], v[40:41]
	v_pk_mul_f32 v[44:45], v[6:7], v[44:45]
	v_pk_add_f32 v[40:41], v[26:27], v[40:41]
	v_pk_fma_f32 v[44:45], v[14:15], v[72:73], v[44:45]
	v_mul_f32_e32 v49, 0xbfb8aa3b, v40
	v_exp_f32_e32 v49, v49
	v_pk_fma_f32 v[44:45], v[22:23], v[70:71], v[44:45]
	v_add_f32_e32 v49, 1.0, v49
	v_rcp_f32_e32 v54, v49
	v_mul_f32_e32 v49, 0xbfb8aa3b, v41
	v_exp_f32_e32 v49, v49
	v_pk_add_f32 v[44:45], v[30:31], v[44:45]
	v_add_f32_e32 v49, 1.0, v49
	v_rcp_f32_e32 v55, v49
	v_pk_fma_f32 v[34:35], v[4:5], v[34:35], v[56:57]
	v_pk_mul_f32 v[40:41], v[40:41], v[54:55]
	v_pk_mul_f32 v[36:37], v[8:9], v[36:37]
	v_pk_mul_f32 v[40:41], v[44:45], v[40:41]
	v_pk_fma_f32 v[34:35], v[20:21], v[58:59], v[34:35]
	v_pk_fma_f32 v[36:37], v[16:17], v[64:65], v[36:37]
	v_pk_add_f32 v[34:35], v[28:29], v[34:35]
	v_pk_fma_f32 v[36:37], v[24:25], v[62:63], v[36:37]
	v_mul_f32_e32 v44, 0xbfb8aa3b, v34
	v_mul_f32_e32 v45, 0xbfb8aa3b, v35
	v_exp_f32_e32 v44, v44
	v_exp_f32_e32 v45, v45
	v_pk_add_f32 v[36:37], v[32:33], v[36:37]
	v_add_f32_e32 v44, 1.0, v44
	v_add_f32_e32 v45, 1.0, v45
	v_rcp_f32_e32 v44, v44
	v_rcp_f32_e32 v45, v45
	s_nop 0
	v_pk_mul_f32 v[34:35], v[34:35], v[44:45]
	s_nop 0
	v_pk_mul_f32 v[34:35], v[36:37], v[34:35]
	v_cvt_pk_bf16_f32 v36, v40, v41
	v_cvt_pk_bf16_f32 v37, v34, v35
	global_store_dwordx2 v[46:47], v[36:37], off
.Lcf1_s1:
	s_or_b64 exec, exec, s[16:17]
	ds_read2_b64 v[34:37], v50 offset0:130 offset1:162
	s_waitcnt lgkmcnt(0)
	v_lshlrev_b32_e32 v56, 16, v34
	v_and_b32_e32 v57, 0xffff0000, v34
	v_add_u32_e32 v34, 1, v51
	v_lshlrev_b32_e32 v52, 16, v35
	v_and_b32_e32 v53, 0xffff0000, v35
	v_lshlrev_b32_e32 v54, 16, v36
	v_and_b32_e32 v55, 0xffff0000, v36
	v_lshlrev_b32_e32 v48, 16, v37
	v_and_b32_e32 v49, 0xffff0000, v37
	v_cmp_gt_i32_e64 s[10:11], s33, v34
	s_and_saveexec_b64 s[16:17], s[10:11]
	s_cbranch_execz .Lcf1_s2
	v_pk_mul_f32 v[40:41], v[10:11], v[66:67]
	v_pk_mul_f32 v[44:45], v[12:13], v[58:59]
	v_add_u32_e32 v74, 2, v0
	v_pk_fma_f32 v[40:41], v[2:3], v[68:69], v[40:41]
	v_pk_fma_f32 v[40:41], v[18:19], v[56:57], v[40:41]
	v_mov_b64_e32 v[68:69], v[72:73]
	v_pk_add_f32 v[40:41], v[26:27], v[40:41]
	v_pk_mul_f32 v[68:69], v[6:7], v[68:69]
	v_mul_f32_e32 v35, 0xbfb8aa3b, v40
	v_exp_f32_e32 v35, v35
	v_pk_fma_f32 v[68:69], v[14:15], v[70:71], v[68:69]
	v_pk_fma_f32 v[68:69], v[22:23], v[54:55], v[68:69]
	v_add_f32_e32 v35, 1.0, v35
	v_rcp_f32_e32 v72, v35
	v_mul_f32_e32 v35, 0xbfb8aa3b, v41
	v_exp_f32_e32 v35, v35
	v_pk_add_f32 v[68:69], v[30:31], v[68:69]
	v_add_f32_e32 v35, 1.0, v35
	v_rcp_f32_e32 v73, v35
	v_pk_fma_f32 v[44:45], v[4:5], v[60:61], v[44:45]
	v_mov_b64_e32 v[60:61], v[52:53]
	v_mov_b64_e32 v[34:35], v[64:65]
	v_pk_fma_f32 v[44:45], v[20:21], v[60:61], v[44:45]
	v_pk_mul_f32 v[34:35], v[8:9], v[34:35]
	v_pk_add_f32 v[44:45], v[28:29], v[44:45]
	v_pk_fma_f32 v[34:35], v[16:17], v[62:63], v[34:35]
	v_pk_fma_f32 v[34:35], v[24:25], v[48:49], v[34:35]
	v_mul_f32_e32 v36, 0xbfb8aa3b, v44
	v_mul_f32_e32 v37, 0xbfb8aa3b, v45
	v_exp_f32_e32 v36, v36
	v_exp_f32_e32 v37, v37
	v_pk_mul_f32 v[40:41], v[40:41], v[72:73]
	v_pk_add_f32 v[34:35], v[32:33], v[34:35]
	v_add_f32_e32 v36, 1.0, v36
	v_add_f32_e32 v37, 1.0, v37
	v_rcp_f32_e32 v36, v36
	v_rcp_f32_e32 v37, v37
	v_pk_mul_f32 v[40:41], v[68:69], v[40:41]
	v_pk_mul_f32 v[36:37], v[44:45], v[36:37]
	s_nop 0
	v_pk_mul_f32 v[34:35], v[34:35], v[36:37]
	v_cvt_pk_bf16_f32 v36, v40, v41
	v_cvt_pk_bf16_f32 v37, v34, v35
	v_mad_i64_i32 v[34:35], s[10:11], v74, s46, v[38:39]
	global_store_dwordx2 v[34:35], v[36:37], off
.Lcf1_s2:
	s_or_b64 exec, exec, s[16:17]
	ds_read2_b64 v[34:37], v50 offset0:195 offset1:227
	v_add_u32_e32 v51, 2, v51
	v_cmp_gt_i32_e64 s[10:11], s33, v51
	s_waitcnt lgkmcnt(0)
	v_lshlrev_b32_e32 v40, 16, v34
	v_and_b32_e32 v41, 0xffff0000, v34
	v_lshlrev_b32_e32 v34, 16, v35
	v_and_b32_e32 v35, 0xffff0000, v35
	v_lshlrev_b32_e32 v44, 16, v36
	v_and_b32_e32 v45, 0xffff0000, v36
	v_lshlrev_b32_e32 v36, 16, v37
	v_and_b32_e32 v37, 0xffff0000, v37
	s_and_saveexec_b64 s[16:17], s[10:11]
	s_cbranch_execz .Lcf1_l
	v_add_u32_e32 v65, 3, v0
	v_pk_mul_f32 v[68:69], v[10:11], v[56:57]
	v_pk_mul_f32 v[72:73], v[12:13], v[52:53]
	v_pk_fma_f32 v[66:67], v[2:3], v[66:67], v[68:69]
	v_pk_fma_f32 v[66:67], v[18:19], v[40:41], v[66:67]
	v_mov_b64_e32 v[68:69], v[70:71]
	v_pk_add_f32 v[66:67], v[26:27], v[66:67]
	v_pk_mul_f32 v[68:69], v[6:7], v[68:69]
	v_mul_f32_e32 v51, 0xbfb8aa3b, v66
	v_exp_f32_e32 v51, v51
	v_pk_fma_f32 v[68:69], v[14:15], v[54:55], v[68:69]
	v_pk_fma_f32 v[68:69], v[22:23], v[44:45], v[68:69]
	v_add_f32_e32 v51, 1.0, v51
	v_rcp_f32_e32 v70, v51
	v_mul_f32_e32 v51, 0xbfb8aa3b, v67
	v_exp_f32_e32 v51, v51
	v_pk_add_f32 v[68:69], v[30:31], v[68:69]
	v_pk_fma_f32 v[58:59], v[4:5], v[58:59], v[72:73]
	v_add_f32_e32 v51, 1.0, v51
	v_rcp_f32_e32 v71, v51
	v_mov_b64_e32 v[60:61], v[62:63]
	v_pk_mul_f32 v[60:61], v[8:9], v[60:61]
	v_pk_mul_f32 v[66:67], v[66:67], v[70:71]
	v_pk_fma_f32 v[60:61], v[16:17], v[48:49], v[60:61]
	v_pk_mul_f32 v[66:67], v[68:69], v[66:67]
	v_mov_b64_e32 v[68:69], v[34:35]
	v_pk_fma_f32 v[58:59], v[20:21], v[68:69], v[58:59]
	v_pk_fma_f32 v[60:61], v[24:25], v[36:37], v[60:61]
	v_pk_add_f32 v[58:59], v[28:29], v[58:59]
	v_pk_add_f32 v[60:61], v[32:33], v[60:61]
	v_mul_f32_e32 v51, 0xbfb8aa3b, v58
	v_exp_f32_e32 v51, v51
	s_nop 0
	v_add_f32_e32 v51, 1.0, v51
	v_rcp_f32_e32 v62, v51
	v_mul_f32_e32 v51, 0xbfb8aa3b, v59
	v_exp_f32_e32 v51, v51
	s_nop 0
	v_add_f32_e32 v51, 1.0, v51
	v_rcp_f32_e32 v63, v51
	s_nop 0
	v_pk_mul_f32 v[58:59], v[58:59], v[62:63]
	s_nop 0
	v_pk_mul_f32 v[58:59], v[60:61], v[58:59]
	v_cvt_pk_bf16_f32 v60, v66, v67
	v_cvt_pk_bf16_f32 v61, v58, v59
	v_mad_i64_i32 v[58:59], s[10:11], v65, s46, v[38:39]
	global_store_dwordx2 v[58:59], v[60:61], off
	s_branch .Lcf1_l
